# last layer w_in GEMM: the 24 units of the partial 4th round run on hgrn workgroups 192-215 after the grid barrier (second pass, counter release/acquire) so the attention workgroups start their units a
# speedup vs baseline: 1.0128x; 1.0062x over previous
_Z10hybrid_fwd4Args:
	s_mov_b32 s3, 0
	v_writelane_b32 v255, s3, 61
	s_mov_b32 s3, 0
	v_writelane_b32 v255, s3, 62
	s_load_dwordx4 s[52:55], s[0:1], 0x90
	s_mov_b32 s78, s2
	s_add_u32 s2, s0, 0xa0
	v_writelane_b32 v252, s0, 0
	s_addc_u32 s3, s1, 0
	v_and_b32_e32 v191, 0x3ff, v0
	v_writelane_b32 v252, s1, 1
	v_writelane_b32 v252, s2, 2
	v_cmp_gt_u32_e32 vcc, 64, v191
	s_nop 0
	v_writelane_b32 v252, s3, 3
	s_and_saveexec_b64 s[0:1], vcc
	v_lshl_add_u32 v1, v191, 2, 0
	v_add_u32_e32 v1, 0x24000, v1
	v_mov_b32_e32 v2, 0
	ds_write_b32 v1, v2
	s_or_b64 exec, exec, s[0:1]
	v_readlane_b32 s0, v252, 0
	v_readlane_b32 s1, v252, 1
	s_load_dwordx2 s[80:81], s[0:1], 0xa0
	s_waitcnt lgkmcnt(0)
	s_barrier
	s_getreg_b32 s0, hwreg(HW_REG_XCC_ID, 0, 4)
	s_and_b32 s4, s0, 15
	v_cmp_eq_u32_e64 s[2:3], 0, v191
	s_mov_b64 s[0:1], exec
	s_nop 0
	v_writelane_b32 v252, s2, 4
	s_nop 1
	v_writelane_b32 v252, s3, 5
	s_and_b64 s[2:3], s[0:1], s[2:3]
	s_mov_b64 exec, s[2:3]
	s_cbranch_execz .LBB0_5
	s_mov_b64 s[2:3], exec
	v_mbcnt_lo_u32_b32 v1, s2, 0
	v_mbcnt_hi_u32_b32 v1, s3, v1
	v_cmp_eq_u32_e32 vcc, 0, v1
	s_and_b64 s[6:7], exec, vcc
	s_mov_b64 exec, s[6:7]
	s_cbranch_execz .LBB0_5
	s_lshl_b32 s5, s4, 8
	s_bcnt1_i32_b64 s2, s[2:3]
	v_mov_b32_e32 v1, s5
	v_mov_b32_e32 v2, s2
	global_atomic_add v1, v2, s[52:53] offset:1024

.LBB0_423:
	v_readlane_b32 s42, v254, 31
	s_andn2_b64 vcc, exec, s[4:5]
	v_readlane_b32 s43, v254, 32
	s_cbranch_vccnz .LBB0_871
	v_writelane_b32 v255, s0, 40
	v_writelane_b32 v255, s1, 41
	v_writelane_b32 v255, s2, 42
	v_writelane_b32 v255, s3, 43
	v_writelane_b32 v255, s4, 44
	v_readlane_b32 s2, v254, 44
	s_nop 3
	s_cmp_eq_u32 s2, 10
	s_cbranch_scc0 .Ll4acq_done_h
	s_cmpk_lt_i32 s78, 0xc0
	s_cbranch_scc1 .Ll4acq_done_h
	v_readfirstlane_b32 s4, v191
	s_nop 3
	s_cmp_lt_u32 s4, 64
	s_cbranch_scc0 .Ll4acq_bar_h
	v_readlane_b32 s0, v254, 10
	v_readlane_b32 s1, v254, 11
	s_nop 3
	s_add_u32 s0, s0, 0x16b00
	s_addc_u32 s1, s1, 0
	s_mov_b32 s3, 0
	s_mov_b64 vcc, exec
	s_mov_b32 exec_lo, 0
	s_brev_b32 exec_hi, 1
.Ll4acq_spin_h:
	global_load_dword v255, v1, s[0:1] sc1
	s_waitcnt vmcnt(0)
	v_readlane_b32 s4, v255, 63
	s_nop 3
	s_cmp_ge_u32 s4, 24
	s_cbranch_scc1 .Ll4acq_got_h
	s_sleep 2
	s_add_u32 s3, s3, 1
	s_cmp_lt_u32 s3, 0x1000
	s_cbranch_scc1 .Ll4acq_spin_h
.Ll4acq_got_h:
	buffer_inv sc1
	s_waitcnt vmcnt(0)
	s_mov_b64 exec, vcc

.Ll4acq_done_h:
	v_readlane_b32 s0, v255, 40
	v_readlane_b32 s1, v255, 41
	v_readlane_b32 s2, v255, 42
	v_readlane_b32 s3, v255, 43
	v_readlane_b32 s4, v255, 44
	s_nop 3
	v_readlane_b32 s2, v252, 20
	v_readlane_b32 s3, v252, 21
	s_mov_b64 s[0:1], -1
	s_and_b64 vcc, exec, s[2:3]
	s_cbranch_vccz .LBB0_426
	v_readlane_b32 s0, v252, 29
	v_readlane_b32 s1, v254, 14
	s_mul_i32 s0, s1, s0
	v_readlane_b32 s1, v252, 19
	s_add_i32 s2, s1, s0
	s_mov_b64 s[0:1], 0

.LBB0_764:
	v_writelane_b32 v255, s0, 40
	v_writelane_b32 v255, s1, 41
	v_writelane_b32 v255, s2, 42
	v_writelane_b32 v255, s3, 43
	v_writelane_b32 v255, s4, 44
	v_readlane_b32 s2, v254, 44
	s_nop 3
	s_cmp_eq_u32 s2, 10
	s_cbranch_scc0 .Ll4acq_done_n
	v_readfirstlane_b32 s4, v191
	s_nop 3
	s_cmp_lt_u32 s4, 64
	s_cbranch_scc0 .Ll4acq_bar_n
	v_readlane_b32 s0, v254, 10
	v_readlane_b32 s1, v254, 11
	s_nop 3
	s_add_u32 s0, s0, 0x16b00
	s_addc_u32 s1, s1, 0
	s_mov_b32 s3, 0
	s_mov_b64 vcc, exec
	s_mov_b32 exec_lo, 0
	s_brev_b32 exec_hi, 1

.Ll4acq_done_n:
	v_readlane_b32 s0, v255, 40
	v_readlane_b32 s1, v255, 41
	v_readlane_b32 s2, v255, 42
	v_readlane_b32 s3, v255, 43
	v_readlane_b32 s4, v255, 44
	s_nop 3
	v_readlane_b32 s0, v252, 37
	v_readlane_b32 s1, v252, 38
	s_andn2_b64 vcc, exec, s[0:1]
	s_cbranch_vccnz .LBB0_870
	v_readlane_b32 s0, v254, 8
	v_readlane_b32 s2, v254, 10
	v_readlane_b32 s3, v254, 11
	s_add_u32 s12, s2, 0x5600800
	s_addc_u32 s13, s3, 0
	s_add_u32 s14, s2, 0x5600b00
	s_addc_u32 s15, s3, 0
	s_mov_b32 s16, s78
	v_readlane_b32 s1, v254, 9
	s_branch .LBB0_767

.LBB0_928:
	s_andn2_b64 vcc, exec, s[0:1]
	s_cbranch_vccnz .LBB0_1331
	v_readlane_b32 s0, v252, 41
	v_readlane_b32 s1, v252, 42
	v_mov_b32_e32 v0, v191
	s_andn2_b64 vcc, exec, s[0:1]
	v_cndmask_b32_e64 v2, 0, 1, s[0:1]
	v_cmp_ne_u32_e64 s[40:41], 1, v2
	v_readfirstlane_b32 s6, v0
	s_cbranch_vccnz .LBB0_931
	v_readlane_b32 s0, v253, 41
	s_mov_b32 s66, s0
	v_readlane_b32 s0, v253, 34
	v_readlane_b32 s2, v254, 44
	v_readlane_b32 s3, v255, 61
	s_nop 3
	s_cmp_eq_u32 s2, 9
	s_cbranch_scc0 .Ll4_first_done
	s_add_i32 s4, s78, 64
	s_and_b32 s4, s4, 0xff
	s_cmp_eq_u32 s3, 1
	s_cselect_b32 s3, 0x300, 0
	s_add_i32 s4, s4, s3
	s_and_b32 s5, s4, 7
	s_lshr_b32 s4, s4, 3
	s_mul_i32 s5, s5, 0x63
	s_add_i32 s4, s4, s5
	s_mul_hi_u32 s5, s4, 0x2aaaaaab
	s_lshr_b32 s5, s5, 4
	s_mul_i32 s3, s5, 0x60
	s_sub_i32 s4, s4, s3
	s_lshl_b32 s5, s5, 3
	s_cmp_lt_u32 s5, 64
	s_cselect_b32 s3, 3, 1
	s_lshr_b32 s66, s4, s3
	s_lshl_b32 s2, s66, s3
	s_sub_i32 s4, s4, s2
	s_add_i32 s0, s5, s4
.Ll4_first_done:
.LBB0_931:
	s_and_b64 vcc, exec, s[40:41]
	s_cbranch_vccnz .LBB0_1331
	v_ashrrev_i32_e32 v3, 31, v0
	v_lshrrev_b32_e32 v3, 26, v3
	v_add_u32_e32 v3, v0, v3
	v_ashrrev_i32_e32 v10, 6, v3
	v_bfe_i32 v3, v0, 27, 1
	v_lshlrev_b32_e32 v2, 4, v0
	v_lshrrev_b32_e32 v3, 22, v3
	v_add_u32_e32 v3, v2, v3
	v_and_b32_e32 v3, 0xfffffc00, v3
	v_sub_u32_e32 v3, v2, v3
	v_lshrrev_b32_e32 v4, 4, v3
	v_bitop3_b32 v3, v4, v3, 32 bitop3:0x6c
	v_ashrrev_i32_e32 v5, 31, v3
	v_lshrrev_b32_e32 v5, 26, v5
	v_add_u32_e32 v5, v3, v5
	v_ashrrev_i32_e32 v11, 6, v5
	v_and_b32_e32 v5, 0xc0, v5
	v_sub_u32_e32 v3, v3, v5
	v_lshlrev_b32_e32 v4, 3, v10
	v_lshlrev_b32_e32 v6, 5, v10
	v_ashrrev_i16_sdwa v3, v220, sext(v3) dst_sel:DWORD dst_unused:UNUSED_PAD src0_sel:DWORD src1_sel:BYTE_0
	v_and_b32_e32 v4, 0x1ffff0, v4
	v_and_b32_e32 v6, 32, v6
	v_bfe_i32 v12, v3, 0, 16
	v_add_u32_e32 v3, v6, v12
	v_add_lshl_u32 v4, v11, v4, 11
	v_add_u32_e32 v2, 0x2000, v2
	v_lshl_add_u32 v134, v3, 1, v4
	v_ashrrev_i32_e32 v3, 31, v2
	v_lshrrev_b32_e32 v3, 22, v3
	v_add_u32_e32 v3, v2, v3
	v_ashrrev_i32_e32 v13, 10, v3
	v_mul_i32_i24_e32 v3, 0x400, v13
	v_readlane_b32 s8, v254, 8
	v_sub_u32_e32 v2, v2, v3
	s_mul_i32 s2, s88, 0x600000
	v_readlane_b32 s10, v254, 10
	v_lshrrev_b32_e32 v3, 4, v2
	s_mul_hi_i32 s1, s88, 0x600000
	v_readlane_b32 s11, v254, 11
	s_add_u32 s2, s10, s2
	v_bitop3_b32 v2, v3, v2, 32 bitop3:0x6c
	s_addc_u32 s1, s11, s1
	v_ashrrev_i32_e32 v4, 31, v2
	v_readlane_b32 s9, v254, 9
	s_add_u32 s8, s2, 0x200000
	v_lshrrev_b32_e32 v4, 26, v4
	s_addc_u32 s9, s1, 0
	s_ashr_i32 s7, s6, 6
	v_add_u32_e32 v4, v2, v4
	s_ashr_i32 s1, s0, 31
	s_ashr_i32 s67, s66, 31
	v_ashrrev_i32_e32 v14, 6, v4
	v_and_b32_e32 v4, 0xc0, v4
	s_ashr_i32 s12, s6, 8
	s_lshl_b32 s10, s7, 10
	s_lshl_b64 s[2:3], s[0:1], 19
	s_lshl_b64 s[4:5], s[66:67], 19
	v_sub_u32_e32 v2, v2, v4
	s_add_u32 s4, s8, s4
	v_lshlrev_b32_e32 v3, 3, v13
	v_lshlrev_b32_e32 v5, 5, v13
	v_ashrrev_i16_sdwa v2, v220, sext(v2) dst_sel:DWORD dst_unused:UNUSED_PAD src0_sel:DWORD src1_sel:BYTE_0
	s_addc_u32 s5, s9, s5
	s_add_i32 s11, s10, 0
	v_and_b32_e32 v3, 0x1ffff0, v3
	v_and_b32_e32 v5, 32, v5
	v_bfe_i32 v15, v2, 0, 16
	s_add_i32 m0, s11, 0x10000
	v_add_u32_e32 v2, v5, v15
	v_add_lshl_u32 v3, v14, v3, 11
	global_load_lds_dwordx4 v134, s[4:5]
	s_add_i32 m0, s11, 0x12000
	v_lshl_add_u32 v136, v2, 1, v3
	s_add_u32 s14, s4, 0x40000
	global_load_lds_dwordx4 v136, s[4:5]
	s_addc_u32 s15, s5, 0
	s_add_i32 m0, s11, 0x14000
	v_readlane_b32 s44, v254, 12
	global_load_lds_dwordx4 v134, s[14:15]
	s_add_i32 m0, s11, 0x16000
	v_readlane_b32 s45, v254, 13
	s_add_u32 s2, s44, s2
	global_load_lds_dwordx4 v136, s[14:15]
	s_addc_u32 s3, s45, s3
	s_add_i32 s14, s11, 0x2000
	s_mov_b32 m0, s11
	s_add_u32 s18, s2, 0x40000
	global_load_lds_dwordx4 v134, s[2:3]
	s_mov_b32 m0, s14
	s_addc_u32 s19, s3, 0
	s_add_i32 s15, s11, 0x4000
	global_load_lds_dwordx4 v136, s[2:3]
	s_mov_b32 m0, s15
	s_add_i32 s16, s11, 0x6000
	global_load_lds_dwordx4 v134, s[18:19]
	s_mov_b32 m0, s16
	s_cmp_eq_u32 s12, 1
	global_load_lds_dwordx4 v136, s[18:19]
	s_mov_b64 s[18:19], s[42:43]
	s_load_dwordx4 s[40:43], s[18:19], 0x48
	s_cselect_b64 s[18:19], -1, 0
	v_mov_b32_e32 v135, v1
	v_mov_b32_e32 v137, v1
	v_writelane_b32 v254, s18, 52
	v_lshl_add_u64 v[8:9], s[4:5], 0, v[134:135]
	v_lshl_add_u64 v[6:7], s[4:5], 0, v[136:137]
	v_lshl_add_u64 v[2:3], s[2:3], 0, v[134:135]
	v_writelane_b32 v254, s19, 53
	s_cmp_lg_u32 s12, 1
	v_lshl_add_u64 v[4:5], s[2:3], 0, v[136:137]
	s_cbranch_scc1 .LBB0_934
	s_barrier

.LBB0_937:
	s_add_i32 s26, s26, 1
	v_readlane_b32 s7, v254, 44
	v_readlane_b32 s1, v255, 61
	s_mul_i32 s6, s26, s80
	s_nop 2
	s_cmp_eq_u32 s1, 1
	s_cselect_b32 s1, 0x300, 0
	s_add_i32 s6, s6, s1
	s_cmp_eq_u32 s7, 9
	s_cselect_b32 s1, 64, 0
	s_add_i32 s1, s1, s78
	s_and_b32 s1, s1, 0xff
	s_add_i32 s6, s6, s1
	s_cmp_eq_u32 s7, 9
	s_cselect_b32 s7, 24, 0
	s_sub_i32 s7, 0x318, s7
	s_cmp_lt_u32 s6, s7
	s_cselect_b64 s[40:41], -1, 0
	s_cbranch_scc0 .LBB0_939
	s_ashr_i32 s1, s6, 31
	s_lshr_b32 s1, s1, 29
	s_add_i32 s1, s6, s1
	s_ashr_i32 s7, s1, 3
	s_and_b32 s1, s1, -8
	s_sub_i32 s1, s6, s1
	s_cmp_lt_i32 s1, 0
	s_cselect_b32 s6, s38, 0x63
	s_mul_i32 s1, s1, s6
	s_add_i32 s1, s1, s7
	s_mul_hi_i32 s6, s1, 0x2aaaaaab
	s_lshr_b32 s7, s6, 31
	s_ashr_i32 s6, s6, 4
	s_add_i32 s6, s6, s7
	s_lshl_b32 s7, s6, 3
	s_sub_i32 s12, 0x42, s7
	s_min_i32 s12, s12, 8
	s_abs_i32 s13, s12
	v_cvt_f32_u32_e32 v0, s13
	s_sub_i32 s28, 0, s13
	s_mulk_i32 s6, 0x60
	s_sub_i32 s1, s1, s6
	v_rcp_iflag_f32_e32 v0, v0
	s_abs_i32 s6, s1
	s_xor_b32 s27, s1, s12
	s_ashr_i32 s27, s27, 31
	v_mul_f32_e32 v0, 0x4f7ffffe, v0
	v_cvt_u32_f32_e32 v0, v0
	s_nop 0
	v_readfirstlane_b32 s29, v0
	s_mul_i32 s28, s28, s29
	s_mul_hi_u32 s28, s29, s28
	s_add_i32 s29, s29, s28
	s_mul_hi_u32 s28, s6, s29
	s_mul_i32 s29, s28, s13
	s_sub_i32 s6, s6, s29
	s_add_i32 s30, s28, 1
	s_sub_i32 s29, s6, s13
	s_cmp_ge_u32 s6, s13
	s_cselect_b32 s28, s30, s28
	s_cselect_b32 s6, s29, s6
	s_add_i32 s29, s28, 1
	s_cmp_ge_u32 s6, s13
	s_cselect_b32 s6, s29, s28
	s_xor_b32 s6, s6, s27
	s_sub_i32 s58, s6, s27
	s_mul_i32 s6, s58, s12
	s_sub_i32 s1, s1, s6
	s_add_i32 s60, s7, s1

.LBB0_1378:
	v_readlane_b32 s0, v255, 61
	s_nop 3
	s_cmp_eq_u32 s0, 1
	s_cbranch_scc0 .Ll4_a
	s_waitcnt vmcnt(0)
	s_barrier
	s_mov_b32 s0, 0
	v_writelane_b32 v255, s0, 61
	v_readfirstlane_b32 s0, v191
	s_nop 3
	s_cmp_ge_u32 s0, 64
	s_cbranch_scc1 .Ll4_nopub
	v_readlane_b32 s0, v254, 10
	v_readlane_b32 s1, v254, 11
	s_nop 3
	s_add_u32 s0, s0, 0x16b00
	s_addc_u32 s1, s1, 0
	s_mov_b64 vcc, exec
	s_mov_b64 exec, 1
	buffer_wbl2 sc1
	s_waitcnt vmcnt(0)
	global_atomic_add v1, v220, s[0:1]
	s_mov_b64 exec, vcc
.Ll4_nopub:
	s_add_i32 s54, s54, 1
	v_readlane_b32 s26, v254, 21
	v_readlane_b32 s36, v254, 25
	v_readlane_b32 s40, v254, 29
	v_readlane_b32 s27, v254, 22
	v_readlane_b32 s37, v254, 26
	v_readlane_b32 s41, v254, 30
	s_branch .Lskip_seam
.Ll4_a:
	s_cmp_eq_u32 s54, 9
	s_cbranch_scc0 .Ll4_b
	s_sub_i32 s0, s78, 0xc0
	s_cmp_lt_u32 s0, 24
	s_cbranch_scc0 .Ll4_b
	s_mov_b32 s0, 1
	v_writelane_b32 v255, s0, 61
	s_sub_i32 s54, s54, 1
.Ll4_b:
	s_add_i32 s54, s54, 1
	s_cmp_eq_u32 s54, 15
	s_cselect_b32 s54, s55, s54
	v_readlane_b32 s26, v254, 21
	v_readlane_b32 s36, v254, 25
	v_readlane_b32 s40, v254, 29
	s_cmp_ge_i32 s54, s55
	v_readlane_b32 s27, v254, 22
	v_readlane_b32 s37, v254, 26
	v_readlane_b32 s41, v254, 30
	s_cbranch_scc1 .Lskip_seam
	v_readlane_b32 s0, v255, 61
	s_nop 3
	s_cmp_eq_u32 s0, 1
	s_cbranch_scc1 .LBB0_1379
	s_cmp_eq_u32 s54, 6
	s_cbranch_scc1 .Lskip_seam
	s_cmp_eq_u32 s54, 9
	s_cbranch_scc0 .LBB0_1379
